# gla_out wave_sum: first four butterfly steps by DPP adds instead of ds_bpermute round trips, on top of v36
# speedup vs baseline: 1.0107x; 1.0054x over previous
; __device__ __forceinline__ unsigned cvt_pk_bf16(float lo, float hi) { const f32x2 v = {lo, hi}; const bf16v2_t b = __builtin_convertvector(v, bf16v2_t); return __builtin_bit_cast(unsigned, b); }
; __device__ __forceinline__ float silu_f(float x) { return x / (1.f + __expf(-x)); }
; __device__ __forceinline__ float wave_sum(float v) {
; #pragma unroll
;     for (int o = 1; o < 64; o <<= 1) v += __shfl_xor(v, o);
;     return v;
; __device__ __forceinline__ void gla_out_phase(const Params& P) {
;     ...
;     for (int idx = blockIdx.x * 8 + wave; idx < NTOK * 4; idx += gridDim.x * 8) {
;         const int row = idx >> 2, h = idx & 3; const size_t off = (size_t)row * 1024 + h * 256 + lane * 4;
;         const f32x4 o = *(const f32x4*)(of + off) + *(const f32x4*)(ob + off);
;         const float ss = wave_sum((o[0] * o[0] + o[1] * o[1]) + (o[2] * o[2] + o[3] * o[3]));
;         const float rstd = rsqrtf(ss * (1.f / 256.f) + 1e-6f);
;         const u32x2 gw = *(const u32x2*)(proj + (size_t)row * INCP + C_BG + h * 256 + lane * 4);
;         const float g0 = __uint_as_float(gw.x << 16), g1 = __uint_as_float(gw.x & 0xffff0000u), g2 = __uint_as_float(gw.y << 16), g3 = __uint_as_float(gw.y & 0xffff0000u);
;         u32x2 w; w.x = cvt_pk_bf16(o[0] * rstd * gn[0] * silu_f(g0), o[1] * rstd * gn[1] * silu_f(g1)); w.y = cvt_pk_bf16(o[2] * rstd * gn[2] * silu_f(g2), o[3] * rstd * gn[3] * silu_f(g3));
;         *(u32x2*)(mix + (size_t)row * D + 1024 + h * 256 + lane * 4) = w;
;     }
.LBB0_628:
	s_waitcnt vmcnt(1)
	v_mov_b32_e32 v20, v68
	v_mov_b32_e32 v21, v69
	v_mov_b32_e32 v22, v70
	v_mov_b32_e32 v23, v71
	v_mov_b32_e32 v24, v72
	v_mov_b32_e32 v25, v73
	v_mov_b32_e32 v26, v74
	v_mov_b32_e32 v27, v75
	v_mov_b32_e32 v36, v84
	v_mov_b32_e32 v37, v85
	v_mov_b32_e32 v30, v78
	v_mov_b32_e32 v31, v79
	v_ashrrev_i32_e32 v68, 2, v5
	v_ashrrev_i32_e32 v69, 31, v68
	v_and_b32_e32 v76, 0x300, v18
	v_mad_i64_i32 v[70:71], s[0:1], v68, s17, v[8:9]
	v_lshlrev_b64 v[72:73], 10, v[68:69]
	v_lshlrev_b32_e32 v86, 1, v76
	v_mad_i64_i32 v[68:69], s[0:1], v68, s19, v[70:71]
	v_or_b32_e32 v72, v72, v76
	v_add_u32_e32 v5, s14, v5
	v_lshl_add_u64 v[74:75], v[70:71], 0, v[86:87]
	v_lshl_add_u64 v[68:69], v[68:69], 0, v[86:87]
	v_or_b32_e32 v72, v72, v4
	v_cmp_lt_i32_e32 vcc, s20, v5
	v_lshl_add_u64 v[70:71], v[74:75], 0, v[10:11]
	v_lshl_add_u64 v[78:79], v[68:69], 0, v[10:11]
	v_lshlrev_b64 v[68:69], 2, v[72:73]
	s_mov_b64 s[98:99], vcc
	v_add_co_u32_e32 v76, vcc, s18, v70
	v_lshl_add_u64 v[80:81], s[36:37], 0, v[68:69]
	s_nop 0
	v_addc_co_u32_e32 v77, vcc, 0, v71, vcc
	v_lshl_add_u64 v[82:83], s[10:11], 0, v[68:69]
	global_load_dwordx4 v[68:71], v[80:81], off
	global_load_dwordx4 v[72:75], v[82:83], off
	global_load_dwordx2 v[84:85], v[76:77], off offset:3072
	v_add_u32_e32 v18, s15, v18
	v_pk_add_f32 v[22:23], v[22:23], v[26:27]
	v_lshlrev_b32_e32 v6, 16, v36
	v_and_b32_e32 v36, 0xffff0000, v36
	v_lshlrev_b32_e32 v38, 16, v37
	v_and_b32_e32 v37, 0xffff0000, v37
	v_mul_f32_e32 v28, 0xbfb8aa3b, v6
	v_mul_f32_e32 v29, 0xbfb8aa3b, v36
	v_mul_f32_e32 v32, 0xbfb8aa3b, v38
	v_mul_f32_e32 v33, 0xbfb8aa3b, v37
	v_pk_add_f32 v[20:21], v[20:21], v[24:25]
	v_exp_f32_e32 v24, v28
	v_exp_f32_e32 v25, v29
	v_exp_f32_e32 v26, v32
	v_exp_f32_e32 v27, v33
	v_pk_mul_f32 v[28:29], v[22:23], v[22:23]
	v_pk_mul_f32 v[32:33], v[20:21], v[20:21]
	v_pk_add_f32 v[24:25], v[24:25], 1.0 op_sel_hi:[1,0]
	v_pk_mov_b32 v[34:35], v[32:33], v[28:29] op_sel:[1,0]
	v_mov_b32_e32 v33, v29
	v_pk_add_f32 v[28:29], v[34:35], v[32:33]
	v_pk_add_f32 v[26:27], v[26:27], 1.0 op_sel_hi:[1,0]
	v_add_f32_e32 v28, v28, v29
	v_div_scale_f32 v32, s[0:1], v25, v25, v36
	v_div_scale_f32 v34, s[0:1], v24, v24, v6
	v_div_scale_f32 v39, s[2:3], v27, v27, v37
	v_rcp_f32_e32 v43, v32
	v_rcp_f32_e32 v44, v34
	v_rcp_f32_e32 v45, v39
	v_div_scale_f32 v41, s[4:5], v26, v26, v38
	v_add_f32_dpp v28, v28, v28 quad_perm:[1,0,3,2] row_mask:0xf bank_mask:0xf
	v_rcp_f32_e32 v46, v41
	v_fma_f32 v29, -v32, v43, 1.0
	v_fma_f32 v47, -v34, v44, 1.0
	v_fma_f32 v48, -v39, v45, 1.0
	v_div_scale_f32 v33, vcc, v36, v25, v36
	v_div_scale_f32 v35, s[0:1], v6, v24, v6
	v_div_scale_f32 v40, s[2:3], v37, v27, v37
	v_fmac_f32_e32 v43, v29, v43
	v_fmac_f32_e32 v44, v47, v44
	v_fmac_f32_e32 v45, v48, v45
	v_mul_f32_e32 v29, v33, v43
	v_mul_f32_e32 v47, v35, v44
	v_mul_f32_e32 v48, v40, v45
	v_fma_f32 v51, -v32, v29, v33
	v_fma_f32 v52, -v34, v47, v35
	v_fma_f32 v53, -v39, v48, v40
	v_fma_f32 v49, -v41, v46, 1.0
	v_fmac_f32_e32 v29, v51, v43
	v_fmac_f32_e32 v47, v52, v44
	v_fmac_f32_e32 v48, v53, v45
	v_div_scale_f32 v42, s[4:5], v38, v26, v38
	v_fmac_f32_e32 v46, v49, v46
	v_fma_f32 v32, -v32, v29, v33
	v_fma_f32 v33, -v34, v47, v35
	v_fma_f32 v34, -v39, v48, v40
	v_add_f32_dpp v39, v28, v28 quad_perm:[2,3,0,1] row_mask:0xf bank_mask:0xf
	v_mul_f32_e32 v49, v42, v46
	v_div_fmas_f32 v28, v32, v43, v29
	v_fma_f32 v54, -v41, v49, v42
	s_mov_b64 vcc, s[0:1]
	v_fmac_f32_e32 v49, v54, v46
	v_div_fixup_f32 v25, v28, v25, v36
	v_div_fmas_f32 v28, v33, v44, v47
	s_mov_b64 vcc, s[2:3]
	v_fma_f32 v35, -v41, v49, v42
	v_div_fixup_f32 v24, v28, v24, v6
	v_div_fmas_f32 v6, v34, v45, v48
	s_mov_b64 vcc, s[4:5]
	v_div_fixup_f32 v27, v6, v27, v37
	v_div_fmas_f32 v6, v35, v46, v49
	v_div_fixup_f32 v26, v6, v26, v38
	v_add_f32_dpp v6, v39, v39 row_half_mirror row_mask:0xf bank_mask:0xf
	v_add_co_u32_e32 v28, vcc, 0x17c18000, v30
	s_nop 0
	s_nop 0
	v_addc_co_u32_e32 v29, vcc, 0, v31, vcc
	v_add_f32_dpp v6, v6, v6 row_mirror row_mask:0xf bank_mask:0xf
	ds_bpermute_b32 v30, v16, v6
	s_waitcnt lgkmcnt(0)
	v_add_f32_e32 v6, v6, v30
	ds_bpermute_b32 v30, v17, v6
	s_waitcnt lgkmcnt(0)
	v_add_f32_e32 v6, v6, v30
	v_fmamk_f32 v6, v6, 0x3b800000, v19
	v_mul_f32_e32 v30, 0x4b800000, v6
	v_cmp_gt_f32_e32 vcc, s16, v6
	s_nop 1
	v_cndmask_b32_e32 v6, v6, v30, vcc
	v_rsq_f32_e32 v6, v6
	s_nop 0
	v_mul_f32_e32 v30, 0x45800000, v6
	v_cndmask_b32_e32 v6, v6, v30, vcc
	v_pk_mul_f32 v[20:21], v[20:21], v[6:7] op_sel_hi:[1,0]
	v_pk_mul_f32 v[22:23], v[22:23], v[6:7] op_sel_hi:[1,0]
	v_pk_mul_f32 v[20:21], v[0:1], v[20:21]
	v_pk_mul_f32 v[22:23], v[2:3], v[22:23]
	v_pk_mul_f32 v[20:21], v[24:25], v[20:21]
	v_pk_mul_f32 v[22:23], v[26:27], v[22:23]
	v_cvt_pk_bf16_f32 v20, v20, v21
	v_cvt_pk_bf16_f32 v21, v22, v23
	global_store_dwordx2 v[28:29], v[20:21], off offset:2048
	s_andn2_b64 exec, exec, s[12:13]
	s_or_b64 s[12:13], s[12:13], s[98:99]
	s_cbranch_execnz .LBB0_628
